# SSD group-norm row loop: gains hoisted, ssq and row loads issued together one row ahead (two register sets)
# speedup vs baseline: 1.0052x; 1.0052x over previous
.LBB0_285:
	s_andn2_b64 vcc, exec, s[0:1]
	s_cbranch_vccnz .LBB0_992
	v_readlane_b32 s0, v255, 2
	s_cmp_lt_i32 s0, 2
	s_mov_b64 s[0:1], -1
	s_cbranch_scc1 .LBB0_940
	v_readlane_b32 s0, v255, 2
	s_cmp_gt_i32 s0, 2
	s_mov_b64 s[0:1], -1
	s_cbranch_scc0 .LBB0_343
	v_mov_b32_e32 v1, v194
	v_mov_b32_e32 v0, v194
	v_readlane_b32 s0, v254, 5
	v_ashrrev_i32_e32 v0, 6, v0
	s_nop 0
	v_add_u32_e32 v0, s0, v0
	s_movk_i32 s0, 0x4400
	v_cmp_gt_i32_e32 vcc, s0, v0
	s_and_saveexec_b64 s[2:3], vcc
	s_cbranch_execz .LBB0_295
	v_readlane_b32 s6, v253, 13
	v_readlane_b32 s0, v254, 63
	v_readlane_b32 s7, v253, 14
	v_readlane_b32 s1, v255, 0
	s_load_dword s20, s[6:7], 0x0
	s_and_b64 s[0:1], s[0:1], exec
	v_readlane_b32 s40, v252, 5
	s_cselect_b32 s0, 0x800, 0
	v_readlane_b32 s46, v252, 11
	v_readlane_b32 s47, v252, 12
	s_add_u32 s0, s46, s0
	v_and_b32_e32 v1, 63, v1
	s_addc_u32 s1, s47, 0
	s_waitcnt vmcnt(11)
	v_lshlrev_b32_e32 v4, 5, v1
	v_mov_b32_e32 v5, v2
	v_lshlrev_b32_e32 v6, 4, v1
	v_mov_b32_e32 v7, v2
	v_cmp_lt_u32_e32 vcc, 31, v1
	s_waitcnt lgkmcnt(0)
	s_lshl_b32 s22, s20, 2
	v_lshl_add_u64 v[4:5], s[0:1], 0, v[4:5]
	v_lshl_add_u64 v[6:7], s[80:81], 0, v[6:7]
	s_mov_b64 s[20:21], 0
	v_readlane_b32 s41, v252, 6
	v_readlane_b32 s42, v252, 7
	v_readlane_b32 s43, v252, 8
	v_readlane_b32 s44, v252, 9
	v_readlane_b32 s45, v252, 10
	v_readlane_b32 s48, v252, 13
	v_readlane_b32 s49, v252, 14
	v_readlane_b32 s50, v252, 15
	v_readlane_b32 s51, v252, 16
	v_readlane_b32 s52, v252, 17
	v_readlane_b32 s53, v252, 18
	v_readlane_b32 s54, v252, 19
	v_readlane_b32 s55, v252, 20
	global_load_dwordx4 v[26:29], v[4:5], off
	global_load_dwordx4 v[30:33], v[4:5], off offset:16
	v_ashrrev_i32_e32 v1, 31, v0
	v_lshl_add_u64 v[8:9], v[0:1], 4, s[90:91]
	v_lshlrev_b64 v[58:59], 12, v[0:1]
	v_lshl_add_u64 v[22:23], v[6:7], 0, v[58:59]
	global_load_dwordx4 v[34:37], v[8:9], off
	global_load_dwordx4 v[40:43], v[22:23], off offset:1024
.Lssd_top:
	v_add_u32_e32 v38, s22, v0
	v_min_i32_e32 v50, 0x43ff, v38
	v_ashrrev_i32_e32 v51, 31, v50
	v_lshl_add_u64 v[8:9], v[50:51], 4, s[90:91]
	v_lshlrev_b64 v[58:59], 12, v[50:51]
	v_lshl_add_u64 v[52:53], v[6:7], 0, v[58:59]
	global_load_dwordx4 v[44:47], v[8:9], off
	global_load_dwordx4 v[54:57], v[52:53], off offset:1024
	s_waitcnt vmcnt(2)
	v_add_f32_e32 v3, v35, v34
	v_add_f32_e32 v12, v37, v36
	v_cndmask_b32_e32 v3, v3, v12, vcc
	v_fmamk_f32 v3, v3, 0x3b800000, v198
	s_mov_b32 s0, 0x800000
	v_cmp_gt_f32_e64 s[0:1], s0, v3
	v_mul_f32_e32 v12, 0x4b800000, v3
	s_nop 0
	v_cndmask_b32_e64 v3, v3, v12, s[0:1]
	v_rsq_f32_e32 v3, v3
	s_nop 0
	v_mul_f32_e32 v12, 0x45800000, v3
	v_cndmask_b32_e64 v20, v3, v12, s[0:1]
	v_lshlrev_b32_e32 v12, 16, v40
	v_and_b32_e32 v13, 0xffff0000, v40
	v_pk_mul_f32 v[12:13], v[20:21], v[12:13] op_sel_hi:[0,1]
	v_pk_mul_f32 v[12:13], v[26:27], v[12:13]
	s_nop 0
	v_cvt_pk_bf16_f32 v40, v12, v13
	v_lshlrev_b32_e32 v12, 16, v41
	v_and_b32_e32 v13, 0xffff0000, v41
	v_pk_mul_f32 v[12:13], v[20:21], v[12:13] op_sel_hi:[0,1]
	v_pk_mul_f32 v[12:13], v[28:29], v[12:13]
	s_nop 0
	v_cvt_pk_bf16_f32 v41, v12, v13
	v_lshlrev_b32_e32 v12, 16, v42
	v_and_b32_e32 v13, 0xffff0000, v42
	v_pk_mul_f32 v[12:13], v[20:21], v[12:13] op_sel_hi:[0,1]
	v_pk_mul_f32 v[12:13], v[12:13], v[30:31]
	s_nop 0
	v_cvt_pk_bf16_f32 v42, v12, v13
	v_lshlrev_b32_e32 v12, 16, v43
	v_and_b32_e32 v13, 0xffff0000, v43
	v_pk_mul_f32 v[12:13], v[20:21], v[12:13] op_sel_hi:[0,1]
	v_pk_mul_f32 v[12:13], v[12:13], v[32:33]
	s_nop 0
	v_cvt_pk_bf16_f32 v43, v12, v13
	global_store_dwordx4 v[22:23], v[40:43], off offset:1024
	v_mov_b32_e32 v0, v38
	v_readfirstlane_b32 s0, v38
	s_cmpk_gt_i32 s0, 0x43ff
	s_cbranch_scc1 .Lssd_done
	v_add_u32_e32 v38, s22, v0
	v_min_i32_e32 v50, 0x43ff, v38
	v_ashrrev_i32_e32 v51, 31, v50
	v_lshl_add_u64 v[8:9], v[50:51], 4, s[90:91]
	v_lshlrev_b64 v[58:59], 12, v[50:51]
	v_lshl_add_u64 v[22:23], v[6:7], 0, v[58:59]
	global_load_dwordx4 v[34:37], v[8:9], off
	global_load_dwordx4 v[40:43], v[22:23], off offset:1024
	s_waitcnt vmcnt(2)
	v_add_f32_e32 v3, v45, v44
	v_add_f32_e32 v12, v47, v46
	v_cndmask_b32_e32 v3, v3, v12, vcc
	v_fmamk_f32 v3, v3, 0x3b800000, v198
	s_mov_b32 s0, 0x800000
	v_cmp_gt_f32_e64 s[0:1], s0, v3
	v_mul_f32_e32 v12, 0x4b800000, v3
	s_nop 0
	v_cndmask_b32_e64 v3, v3, v12, s[0:1]
	v_rsq_f32_e32 v3, v3
	s_nop 0
	v_mul_f32_e32 v12, 0x45800000, v3
	v_cndmask_b32_e64 v20, v3, v12, s[0:1]
	v_lshlrev_b32_e32 v12, 16, v54
	v_and_b32_e32 v13, 0xffff0000, v54
	v_pk_mul_f32 v[12:13], v[20:21], v[12:13] op_sel_hi:[0,1]
	v_pk_mul_f32 v[12:13], v[26:27], v[12:13]
	s_nop 0
	v_cvt_pk_bf16_f32 v54, v12, v13
	v_lshlrev_b32_e32 v12, 16, v55
	v_and_b32_e32 v13, 0xffff0000, v55
	v_pk_mul_f32 v[12:13], v[20:21], v[12:13] op_sel_hi:[0,1]
	v_pk_mul_f32 v[12:13], v[28:29], v[12:13]
	s_nop 0
	v_cvt_pk_bf16_f32 v55, v12, v13
	v_lshlrev_b32_e32 v12, 16, v56
	v_and_b32_e32 v13, 0xffff0000, v56
	v_pk_mul_f32 v[12:13], v[20:21], v[12:13] op_sel_hi:[0,1]
	v_pk_mul_f32 v[12:13], v[12:13], v[30:31]
	s_nop 0
	v_cvt_pk_bf16_f32 v56, v12, v13
	v_lshlrev_b32_e32 v12, 16, v57
	v_and_b32_e32 v13, 0xffff0000, v57
	v_pk_mul_f32 v[12:13], v[20:21], v[12:13] op_sel_hi:[0,1]
	v_pk_mul_f32 v[12:13], v[12:13], v[32:33]
	s_nop 0
	v_cvt_pk_bf16_f32 v57, v12, v13
	global_store_dwordx4 v[52:53], v[54:57], off offset:1024
	v_mov_b32_e32 v0, v38
	v_readfirstlane_b32 s0, v38
	s_cmpk_gt_i32 s0, 0x43ff
	s_cbranch_scc0 .Lssd_top
.Lssd_done:
	s_waitcnt vmcnt(0)
.LBB0_295:
	s_or_b64 exec, exec, s[2:3]
	v_readlane_b32 s6, v253, 13
	s_waitcnt vmcnt(1)
	v_mov_b32_e32 v68, v194
	s_movk_i32 s0, 0x400
	s_movk_i32 s2, 0x400
	s_movk_i32 s1, 0x400
	v_readlane_b32 s7, v253, 14
	s_load_dword s3, s[6:7], 0x10
	s_load_dword s22, s[6:7], 0x0
	s_waitcnt lgkmcnt(0)
	s_lshr_b32 s3, s3, 16
	s_cmp_lg_u32 s3, 0
	s_cselect_b64 s[20:21], -1, 0
	s_cmp_lg_u64 s[20:21], 0
	s_addc_u32 s3, s22, 0
	s_lshr_b32 s46, s3, 3
	v_readlane_b32 s3, v254, 36
	s_mul_i32 s52, s46, s3
	v_readlane_b32 s3, v254, 30
	s_add_i32 s52, s52, s3
	s_cmpk_gt_i32 s52, 0x10ff
	s_cbranch_scc1 .LBB0_319
	v_readlane_b32 s6, v254, 63
	s_ashr_i32 s47, s1, 6
	v_readlane_b32 s7, v255, 0
	s_and_b64 s[20:21], s[6:7], exec
	s_mov_b32 s1, 0x2080000
	v_readlane_b32 s8, v252, 37
	s_cselect_b32 s1, s1, 0xc40000
	v_readlane_b32 s16, v252, 45
	v_readlane_b32 s17, v252, 46
	s_add_u32 s24, s16, s1
	s_addc_u32 s25, s17, 0
	s_ashr_i32 s1, s52, 31
	s_lshr_b32 s1, s1, 24
	v_readlane_b32 s20, v252, 49
	s_add_i32 s1, s52, s1
	s_ashr_i32 s1, s1, 8
	s_lshl_b32 s20, s52, 7
	v_lshlrev_b32_e32 v0, 3, v68
	v_readlane_b32 s21, v252, 50
	v_ashrrev_i32_e32 v3, 3, v68
	s_lshl_b32 s3, s1, 10
	s_and_b32 s20, s20, 0x380
	v_and_b32_e32 v0, 56, v0
	v_lshrrev_b32_e32 v132, 4, v68
	v_xor_b32_e32 v132, v132, v68
	v_and_b32_e32 v132, 7, v132
	v_lshlrev_b32_e32 v0, 3, v132
	v_mov_b32_e32 v1, v2
	s_or_b32 s55, s3, s20
	s_lshl_b32 s1, s1, 12
	s_lshl_b32 s3, s52, 4
	v_mad_i64_i32 v[4:5], s[20:21], s0, v3, v[0:1]
	v_mad_i64_i32 v[0:1], s[20:21], s2, v3, v[0:1]
	s_sub_i32 s1, s3, s1
	s_mul_hi_i32 s21, s55, s0
	s_mul_i32 s20, s55, s0
	s_and_b32 s53, s1, 0xffffff80
	s_ashr_i32 s1, s0, 31
	s_ashr_i32 s3, s2, 31
	s_lshl_b64 s[20:21], s[20:21], 1
	s_add_u32 s20, s76, s20
	s_addc_u32 s21, s77, s21
	v_lshlrev_b64 v[70:71], 1, v[4:5]
	v_lshl_add_u64 v[144:145], s[20:21], 0, v[70:71]
	s_mul_hi_i32 s21, s53, s2
	s_mul_i32 s20, s53, s2
	s_lshl_b64 s[20:21], s[20:21], 1
	s_add_u32 s20, s24, s20
	s_addc_u32 s21, s25, s21
	s_waitcnt vmcnt(0)
	v_lshlrev_b64 v[72:73], 1, v[0:1]
	v_readlane_b32 s22, v252, 51
	v_readlane_b32 s23, v252, 52
	v_lshl_add_u64 v[146:147], s[20:21], 0, v[72:73]
	s_lshl_b64 s[20:21], s[0:1], 6
	v_lshl_add_u64 v[0:1], v[144:145], 0, s[20:21]
	s_lshl_b64 s[22:23], s[2:3], 6
	s_waitcnt vmcnt(0)
	v_lshl_add_u64 v[36:37], v[0:1], 0, s[20:21]
	s_waitcnt vmcnt(0)
	v_lshl_add_u64 v[56:57], v[146:147], 0, s[22:23]
	v_lshl_add_u64 v[40:41], v[36:37], 0, s[20:21]
	s_waitcnt vmcnt(0)
	v_lshl_add_u64 v[60:61], v[56:57], 0, s[22:23]
	s_waitcnt vmcnt(0)
	v_lshl_add_u64 v[64:65], v[60:61], 0, s[22:23]
	s_bfe_u32 s100, s101, 0x20002
	s_lshl_b32 s100, s100, 10
	s_andn2_b32 s101, s101, 0x6000000
	s_bfe_u32 vcc_lo, s101, 0x80008
	s_add_u32 vcc_lo, vcc_lo, 0
	s_add_u32 vcc_hi, s47, -1
	s_and_b32 vcc_lo, vcc_lo, vcc_hi
	s_lshl_b32 vcc_lo, vcc_lo, 7
	s_mov_b32 vcc_hi, 0
	v_lshl_add_u64 v[20:21], v[144:145], 0, vcc
	s_add_u32 m0, s100, 0x0
	s_nop 0
	global_load_lds_dwordx4 v[20:21], off
	v_lshl_add_u64 v[20:21], v[0:1], 0, vcc
	s_add_u32 m0, s100, 0x1000
	s_nop 0
	global_load_lds_dwordx4 v[20:21], off
	v_lshl_add_u64 v[20:21], v[36:37], 0, vcc
	s_add_u32 m0, s100, 0x2000
	s_nop 0
	global_load_lds_dwordx4 v[20:21], off
	v_lshl_add_u64 v[20:21], v[40:41], 0, vcc
	s_add_u32 m0, s100, 0x3000
	s_nop 0
	global_load_lds_dwordx4 v[20:21], off
	v_lshl_add_u64 v[20:21], v[146:147], 0, vcc
	s_add_u32 m0, s100, 0x4000
	s_nop 0
	global_load_lds_dwordx4 v[20:21], off
	v_lshl_add_u64 v[20:21], v[56:57], 0, vcc
	s_add_u32 m0, s100, 0x5000
	s_nop 0
	global_load_lds_dwordx4 v[20:21], off
	v_lshl_add_u64 v[20:21], v[60:61], 0, vcc
	s_add_u32 m0, s100, 0x6000
	s_nop 0
	global_load_lds_dwordx4 v[20:21], off
	v_lshl_add_u64 v[20:21], v[64:65], 0, vcc
	s_add_u32 m0, s100, 0x7000
	s_nop 0
	global_load_lds_dwordx4 v[20:21], off
	s_bfe_u32 vcc_lo, s101, 0x80008
	s_add_u32 vcc_lo, vcc_lo, 1
	s_add_u32 vcc_hi, s47, -1
	s_and_b32 vcc_lo, vcc_lo, vcc_hi
	s_lshl_b32 vcc_lo, vcc_lo, 7
	s_mov_b32 vcc_hi, 0
	v_lshl_add_u64 v[20:21], v[144:145], 0, vcc
	s_add_u32 m0, s100, 0x8000
	s_nop 0
	global_load_lds_dwordx4 v[20:21], off
	v_lshl_add_u64 v[20:21], v[0:1], 0, vcc
	s_add_u32 m0, s100, 0x9000
	s_nop 0
	global_load_lds_dwordx4 v[20:21], off
	v_lshl_add_u64 v[20:21], v[36:37], 0, vcc
	s_add_u32 m0, s100, 0xa000
	s_nop 0
	global_load_lds_dwordx4 v[20:21], off
	v_lshl_add_u64 v[20:21], v[40:41], 0, vcc
	s_add_u32 m0, s100, 0xb000
	s_nop 0
	global_load_lds_dwordx4 v[20:21], off
	v_lshl_add_u64 v[20:21], v[146:147], 0, vcc
	s_add_u32 m0, s100, 0xc000
	s_nop 0
	global_load_lds_dwordx4 v[20:21], off
	v_lshl_add_u64 v[20:21], v[56:57], 0, vcc
	s_add_u32 m0, s100, 0xd000
	s_nop 0
	global_load_lds_dwordx4 v[20:21], off
	v_lshl_add_u64 v[20:21], v[60:61], 0, vcc
	s_add_u32 m0, s100, 0xe000
	s_nop 0
	global_load_lds_dwordx4 v[20:21], off
	v_lshl_add_u64 v[20:21], v[64:65], 0, vcc
	s_add_u32 m0, s100, 0xf000
	s_nop 0
	global_load_lds_dwordx4 v[20:21], off
	v_lshrrev_b32_e32 v1, 1, v3
	v_xor_b32_e32 v1, v1, v68
	v_lshlrev_b32_e32 v0, 7, v3
	v_lshlrev_b32_e32 v1, 4, v1
	s_movk_i32 s1, 0x70
	v_lshrrev_b32_e32 v69, 4, v68
	v_bfe_u32 v74, v68, 4, 2
	v_and_or_b32 v3, v1, s1, v0
	v_lshl_add_u64 v[0:1], s[76:77], 0, v[70:71]
	v_bfe_u32 v70, v68, 1, 3
	v_bitop3_b32 v69, v69, v70, 3 bitop3:0x6c
	v_lshlrev_b32_e32 v71, 6, v68
	v_lshlrev_b32_e32 v68, 7, v68
	v_bitop3_b32 v70, v74, v70, 4 bitop3:0x36
	v_lshl_add_u64 v[138:139], s[24:25], 0, v[72:73]
	v_lshlrev_b32_e32 v69, 4, v69
	v_and_b32_e32 v71, 0xffffe000, v71
	v_and_b32_e32 v72, 0x780, v68
	v_and_b32_e32 v68, 0x2000, v68
	v_lshlrev_b32_e32 v70, 4, v70
	s_cmp_gt_i32 s47, 0
	v_or_b32_e32 v73, v69, v71
	v_or_b32_e32 v69, v69, v68
	v_or_b32_e32 v71, v70, v71
	v_or_b32_e32 v68, v70, v68
	s_mov_b32 s49, 0
	s_cselect_b64 s[24:25], -1, 0
	v_add_u32_e32 v137, v73, v72
	v_add_u32_e32 v188, v69, v72
	v_add_u32_e32 v189, v71, v72
	v_add_u32_e32 v190, v68, v72
	s_mov_b32 s1, 0
	s_mov_b32 s3, 0
	v_readlane_b32 s9, v252, 38
	v_readlane_b32 s10, v252, 39
	v_readlane_b32 s11, v252, 40
	v_readlane_b32 s12, v252, 41
	v_readlane_b32 s13, v252, 42
	v_readlane_b32 s14, v252, 43
	v_readlane_b32 s15, v252, 44
	v_readlane_b32 s18, v252, 47
	v_readlane_b32 s19, v252, 48
	s_bfe_u32 vcc_lo, s101, 0x10001
	v_and_b32_e32 v20, 15, v194
	v_lshrrev_b32_e32 v21, 1, v20
	v_bfe_u32 v22, v194, 4, 2
	v_xor_b32_e32 v21, v21, v22
	v_lshlrev_b32_e32 v21, 4, v21
	v_lshl_or_b32 v250, v20, 7, v21
	v_mov_b32_e32 v22, vcc_lo
	v_lshl_or_b32 v22, v22, 13, v250
	v_or_b32_e32 v251, 0x4000, v22
	v_and_b32_e32 v20, 63, v194
	v_mov_b32_e32 v21, vcc_lo
	v_lshlrev_b32_e32 v21, 4, v21
	v_lshrrev_b32_e32 v22, 3, v20
	v_add_u32_e32 v21, v21, v22
	v_lshrrev_b32_e32 v22, 4, v20
	v_and_b32_e32 v23, 7, v20
	v_xor_b32_e32 v24, v23, v22
	v_lshlrev_b32_e32 v24, 4, v24
	v_or_b32_e32 v22, 4, v22
	v_xor_b32_e32 v25, v23, v22
	v_lshlrev_b32_e32 v25, 4, v25
	s_movk_i32 s98, 0x800
	s_movk_i32 s99, 0x800
	v_add_u32_e32 v26, 0, v21
	v_mad_u32_u24 v4, v26, s98, v24
	v_add_u32_e32 v26, 8, v21
	v_mad_u32_u24 v5, v26, s98, v25
	v_add_u32_e32 v26, 32, v21
	v_mad_u32_u24 v6, v26, s98, v24
	v_add_u32_e32 v26, 40, v21
	v_mad_u32_u24 v7, v26, s98, v25
	v_add_u32_e32 v26, 64, v21
	v_mad_u32_u24 v8, v26, s98, v24
	v_add_u32_e32 v26, 72, v21
	v_mad_u32_u24 v9, v26, s98, v25
	v_add_u32_e32 v26, 96, v21
	v_mad_u32_u24 v10, v26, s98, v24
	v_add_u32_e32 v26, 104, v21
	v_mad_u32_u24 v11, v26, s98, v25
	v_add_u32_e32 v26, 0, v21
	v_mad_u32_u24 v12, v26, s99, v24
	v_add_u32_e32 v26, 8, v21
	v_mad_u32_u24 v13, v26, s99, v25
	v_add_u32_e32 v26, 32, v21
	v_mad_u32_u24 v14, v26, s99, v24
	v_add_u32_e32 v26, 40, v21
	v_mad_u32_u24 v15, v26, s99, v25
	v_add_u32_e32 v26, 64, v21
	v_mad_u32_u24 v16, v26, s99, v24
	v_add_u32_e32 v26, 72, v21
	v_mad_u32_u24 v17, v26, s99, v25
	v_add_u32_e32 v26, 96, v21
	v_mad_u32_u24 v18, v26, s99, v24
	v_add_u32_e32 v26, 104, v21
	v_mad_u32_u24 v19, v26, s99, v25
	s_bfe_u32 vcc_hi, s101, 0x20002
	s_lshl_b32 vcc_hi, vcc_hi, 3
	s_mul_i32 s98, s98, vcc_hi
	s_mul_i32 s99, s99, vcc_hi
	s_lshl_b32 vcc_hi, vcc_hi, 3
	s_and_b32 vcc_hi, vcc_hi, 0x70
	s_add_u32 s98, s98, vcc_hi
	s_add_u32 s99, s99, vcc_hi
	s_lshl_b32 s100, vcc_lo, 11
	s_bitcmp1_b32 s101, 0
	s_cselect_b32 s100, -1, s100
	s_waitcnt vmcnt(0) lgkmcnt(0)
	s_barrier
	s_branch .LBB0_299
